# FFN-in SwiGLU epilogue stores made write-through (sc1); norm-loop stores sc1; pipelined norm loop + QKV rope pipelining
# speedup vs baseline: 1.0057x; 1.0001x over previous
; __device__ __forceinline__ unsigned cvt_pk_bf16(float lo, float hi) { const cvt_f32x2 v = {lo, hi}; return __builtin_bit_cast(unsigned, __builtin_convertvector(v, cvt_bf16x2)); }
; __device__ __forceinline__ float silu_mul(float a, float b) { return a * __builtin_amdgcn_rcpf(1.0f + __builtin_amdgcn_exp2f(-1.4426950408889634f * a)) * b; }
;     __device__ __forceinline__ void operator()(const f32x4 (&acc)[2][2][4][2], const Unit& u, int wr, int wc, int fr, int fq) const {
;         const int row0 = u.pm * BM + wr * 64 + fr; const int col0 = u.pn * HALF + wc * 32 + 8 * fq;
; #pragma unroll
;         for (int ai = 0; ai < 2; ++ai)
; #pragma unroll
;             for (int m = 0; m < 4; ++m) { bf16_t* rowp = O + (size_t)(row0 + ai * HALF + m * 16) * ldc + col0;
;                 const f32x4 a0 = acc[ai][0][m][0], a1 = acc[ai][0][m][1], b0 = acc[ai][1][m][0], b1 = acc[ai][1][m][1];
;                 u32x4 w; w.x = cvt_pk_bf16(silu_mul(a0[0], b0[0]), silu_mul(a0[1], b0[1])); w.y = cvt_pk_bf16(silu_mul(a0[2], b0[2]), silu_mul(a0[3], b0[3]));
;                 w.z = cvt_pk_bf16(silu_mul(a1[0], b1[0]), silu_mul(a1[1], b1[1])); w.w = cvt_pk_bf16(silu_mul(a1[2], b1[2]), silu_mul(a1[3], b1[3]));
;                 *(u32x4*)rowp = w; }
.LBB0_310:
	v_mul_f32_e32 v147, 0xbfb8aa3b, v124
	v_exp_f32_e32 v147, v147
	v_lshl_add_u32 v146, s3, 8, v142
	v_lshl_or_b32 v140, s2, 7, v144
	v_ashrrev_i32_e32 v141, 31, v140
	v_add_f32_e32 v147, 1.0, v147
	v_rcp_f32_e32 v150, v147
	v_mul_f32_e32 v147, 0xbfb8aa3b, v125
	v_exp_f32_e32 v147, v147
	v_mov_b64_e32 v[138:139], s[58:59]
	v_mad_i64_i32 v[148:149], s[2:3], v146, s48, v[138:139]
	v_add_f32_e32 v147, 1.0, v147
	v_rcp_f32_e32 v151, v147
	v_lshlrev_b64 v[140:141], 1, v[140:141]
	v_lshl_add_u64 v[148:149], v[148:149], 0, v[140:141]
	s_mov_b64 s[4:5], -1
	v_pk_mul_f32 v[124:125], v[124:125], v[150:151]
	s_andn2_b64 vcc, exec, s[6:7]
	v_pk_mul_f32 v[120:121], v[124:125], v[120:121]
	s_nop 0
	v_cvt_pk_bf16_f32 v120, v120, v121
	v_mul_f32_e32 v121, 0xbfb8aa3b, v126
	v_exp_f32_e32 v121, v121
	s_nop 0
	v_add_f32_e32 v121, 1.0, v121
	v_rcp_f32_e32 v124, v121
	v_mul_f32_e32 v121, 0xbfb8aa3b, v127
	v_exp_f32_e32 v121, v121
	s_nop 0
	v_add_f32_e32 v121, 1.0, v121
	v_rcp_f32_e32 v125, v121
	s_nop 0
	v_pk_mul_f32 v[124:125], v[126:127], v[124:125]
	s_nop 0
	v_pk_mul_f32 v[122:123], v[124:125], v[122:123]
	s_nop 0
	v_cvt_pk_bf16_f32 v121, v122, v123
	v_mul_f32_e32 v122, 0xbfb8aa3b, v116
	v_mul_f32_e32 v123, 0xbfb8aa3b, v117
	v_exp_f32_e32 v122, v122
	v_exp_f32_e32 v123, v123
	v_add_f32_e32 v122, 1.0, v122
	v_add_f32_e32 v123, 1.0, v123
	v_rcp_f32_e32 v122, v122
	v_rcp_f32_e32 v123, v123
	s_nop 0
	v_pk_mul_f32 v[116:117], v[116:117], v[122:123]
	s_nop 0
	v_pk_mul_f32 v[112:113], v[116:117], v[112:113]
	s_nop 0
	v_cvt_pk_bf16_f32 v122, v112, v113
	v_mul_f32_e32 v112, 0xbfb8aa3b, v118
	v_mul_f32_e32 v113, 0xbfb8aa3b, v119
	v_exp_f32_e32 v112, v112
	v_exp_f32_e32 v113, v113
	v_add_f32_e32 v112, 1.0, v112
	v_add_f32_e32 v113, 1.0, v113
	v_rcp_f32_e32 v112, v112
	v_rcp_f32_e32 v113, v113
	s_nop 0
	v_pk_mul_f32 v[112:113], v[118:119], v[112:113]
	s_nop 0
	v_pk_mul_f32 v[112:113], v[112:113], v[114:115]
	v_mul_f32_e32 v114, 0xbfb8aa3b, v108
	v_mul_f32_e32 v115, 0xbfb8aa3b, v109
	v_exp_f32_e32 v114, v114
	v_exp_f32_e32 v115, v115
	v_cvt_pk_bf16_f32 v123, v112, v113
	v_or_b32_e32 v112, 16, v146
	v_add_f32_e32 v114, 1.0, v114
	v_add_f32_e32 v115, 1.0, v115
	v_rcp_f32_e32 v114, v114
	v_rcp_f32_e32 v115, v115
	v_mad_i64_i32 v[112:113], s[2:3], v112, s48, v[138:139]
	v_lshl_add_u64 v[112:113], v[112:113], 0, v[140:141]
	v_pk_mul_f32 v[108:109], v[108:109], v[114:115]
	global_store_dwordx4 v[148:149], v[120:123], off sc1
	v_pk_mul_f32 v[104:105], v[108:109], v[104:105]
	s_nop 0
	v_cvt_pk_bf16_f32 v104, v104, v105
	v_mul_f32_e32 v105, 0xbfb8aa3b, v110
	v_exp_f32_e32 v105, v105
	s_nop 0
	v_add_f32_e32 v105, 1.0, v105
	v_rcp_f32_e32 v108, v105
	v_mul_f32_e32 v105, 0xbfb8aa3b, v111
	v_exp_f32_e32 v105, v105
	s_nop 0
	v_add_f32_e32 v105, 1.0, v105
	v_rcp_f32_e32 v109, v105
	s_nop 0
	v_pk_mul_f32 v[108:109], v[110:111], v[108:109]
	s_nop 0
	v_pk_mul_f32 v[106:107], v[108:109], v[106:107]
	s_nop 0
	v_cvt_pk_bf16_f32 v105, v106, v107
	v_mul_f32_e32 v106, 0xbfb8aa3b, v100
	v_mul_f32_e32 v107, 0xbfb8aa3b, v101
	v_exp_f32_e32 v106, v106
	v_exp_f32_e32 v107, v107
	v_add_f32_e32 v106, 1.0, v106
	v_add_f32_e32 v107, 1.0, v107
	v_rcp_f32_e32 v106, v106
	v_rcp_f32_e32 v107, v107
	s_nop 0
	v_pk_mul_f32 v[100:101], v[100:101], v[106:107]
	s_nop 0
	v_pk_mul_f32 v[96:97], v[100:101], v[96:97]
	s_nop 0
	v_cvt_pk_bf16_f32 v106, v96, v97
	v_mul_f32_e32 v96, 0xbfb8aa3b, v102
	v_mul_f32_e32 v97, 0xbfb8aa3b, v103
	v_exp_f32_e32 v96, v96
	v_exp_f32_e32 v97, v97
	v_add_f32_e32 v96, 1.0, v96
	v_add_f32_e32 v97, 1.0, v97
	v_rcp_f32_e32 v96, v96
	v_rcp_f32_e32 v97, v97
	s_nop 0
	v_pk_mul_f32 v[96:97], v[102:103], v[96:97]
	s_nop 0
	v_pk_mul_f32 v[96:97], v[96:97], v[98:99]
	v_mul_f32_e32 v98, 0xbfb8aa3b, v92
	v_mul_f32_e32 v99, 0xbfb8aa3b, v93
	v_exp_f32_e32 v98, v98
	v_exp_f32_e32 v99, v99
	v_cvt_pk_bf16_f32 v107, v96, v97
	v_or_b32_e32 v96, 32, v146
	v_add_f32_e32 v98, 1.0, v98
	v_add_f32_e32 v99, 1.0, v99
	v_rcp_f32_e32 v98, v98
	v_rcp_f32_e32 v99, v99
	v_mad_i64_i32 v[96:97], s[2:3], v96, s48, v[138:139]
	v_lshl_add_u64 v[96:97], v[96:97], 0, v[140:141]
	v_pk_mul_f32 v[92:93], v[92:93], v[98:99]
	global_store_dwordx4 v[112:113], v[104:107], off sc1
	v_pk_mul_f32 v[88:89], v[92:93], v[88:89]
	s_nop 0
	v_cvt_pk_bf16_f32 v88, v88, v89
	v_mul_f32_e32 v89, 0xbfb8aa3b, v94
	v_exp_f32_e32 v89, v89
	s_nop 0
	v_add_f32_e32 v89, 1.0, v89
	v_rcp_f32_e32 v92, v89
	v_mul_f32_e32 v89, 0xbfb8aa3b, v95
	v_exp_f32_e32 v89, v89
	s_nop 0
	v_add_f32_e32 v89, 1.0, v89
	v_rcp_f32_e32 v93, v89
	s_nop 0
	v_pk_mul_f32 v[92:93], v[94:95], v[92:93]
	s_nop 0
	v_pk_mul_f32 v[90:91], v[92:93], v[90:91]
	s_nop 0
	v_cvt_pk_bf16_f32 v89, v90, v91
	v_mul_f32_e32 v90, 0xbfb8aa3b, v84
	v_mul_f32_e32 v91, 0xbfb8aa3b, v85
	v_exp_f32_e32 v90, v90
	v_exp_f32_e32 v91, v91
	v_add_f32_e32 v90, 1.0, v90
	v_add_f32_e32 v91, 1.0, v91
	v_rcp_f32_e32 v90, v90
	v_rcp_f32_e32 v91, v91
	s_nop 0
	v_pk_mul_f32 v[84:85], v[84:85], v[90:91]
	s_nop 0
	v_pk_mul_f32 v[80:81], v[84:85], v[80:81]
	s_nop 0
	v_cvt_pk_bf16_f32 v90, v80, v81
	v_mul_f32_e32 v80, 0xbfb8aa3b, v86
	v_mul_f32_e32 v81, 0xbfb8aa3b, v87
	v_exp_f32_e32 v80, v80
	v_exp_f32_e32 v81, v81
	v_add_f32_e32 v80, 1.0, v80
	v_add_f32_e32 v81, 1.0, v81
	v_rcp_f32_e32 v80, v80
	v_rcp_f32_e32 v81, v81
	s_nop 0
	v_pk_mul_f32 v[80:81], v[86:87], v[80:81]
	s_nop 0
	v_pk_mul_f32 v[80:81], v[80:81], v[82:83]
	v_mul_f32_e32 v82, 0xbfb8aa3b, v76
	v_mul_f32_e32 v83, 0xbfb8aa3b, v77
	v_exp_f32_e32 v82, v82
	v_exp_f32_e32 v83, v83
	v_cvt_pk_bf16_f32 v91, v80, v81
	v_or_b32_e32 v80, 48, v146
	v_add_f32_e32 v82, 1.0, v82
	v_add_f32_e32 v83, 1.0, v83
	v_rcp_f32_e32 v82, v82
	v_rcp_f32_e32 v83, v83
; __device__ __forceinline__ unsigned cvt_pk_bf16(float lo, float hi) { const cvt_f32x2 v = {lo, hi}; return __builtin_bit_cast(unsigned, __builtin_convertvector(v, cvt_bf16x2)); }
; __device__ __forceinline__ float silu_mul(float a, float b) { return a * __builtin_amdgcn_rcpf(1.0f + __builtin_amdgcn_exp2f(-1.4426950408889634f * a)) * b; }
;     __device__ __forceinline__ void operator()(const f32x4 (&acc)[2][2][4][2], const Unit& u, int wr, int wc, int fr, int fq) const {
;     ...
;             for (int m = 0; m < 4; ++m) { bf16_t* rowp = O + (size_t)(row0 + ai * HALF + m * 16) * ldc + col0;
;                 const f32x4 a0 = acc[ai][0][m][0], a1 = acc[ai][0][m][1], b0 = acc[ai][1][m][0], b1 = acc[ai][1][m][1];
;                 u32x4 w; w.x = cvt_pk_bf16(silu_mul(a0[0], b0[0]), silu_mul(a0[1], b0[1])); w.y = cvt_pk_bf16(silu_mul(a0[2], b0[2]), silu_mul(a0[3], b0[3]));
;                 w.z = cvt_pk_bf16(silu_mul(a1[0], b1[0]), silu_mul(a1[1], b1[1])); w.w = cvt_pk_bf16(silu_mul(a1[2], b1[2]), silu_mul(a1[3], b1[3]));
;                 *(u32x4*)rowp = w; }
	v_mad_i64_i32 v[80:81], s[2:3], v80, s48, v[138:139]
	v_lshl_add_u64 v[80:81], v[80:81], 0, v[140:141]
	v_pk_mul_f32 v[76:77], v[76:77], v[82:83]
	global_store_dwordx4 v[96:97], v[88:91], off sc1
	v_pk_mul_f32 v[72:73], v[76:77], v[72:73]
	s_nop 0
	v_cvt_pk_bf16_f32 v72, v72, v73
	v_mul_f32_e32 v73, 0xbfb8aa3b, v78
	v_exp_f32_e32 v73, v73
	s_nop 0
	v_add_f32_e32 v73, 1.0, v73
	v_rcp_f32_e32 v76, v73
	v_mul_f32_e32 v73, 0xbfb8aa3b, v79
	v_exp_f32_e32 v73, v73
	s_nop 0
	v_add_f32_e32 v73, 1.0, v73
	v_rcp_f32_e32 v77, v73
	s_nop 0
	v_pk_mul_f32 v[76:77], v[78:79], v[76:77]
	s_nop 0
	v_pk_mul_f32 v[74:75], v[76:77], v[74:75]
	s_nop 0
	v_cvt_pk_bf16_f32 v73, v74, v75
	v_mul_f32_e32 v74, 0xbfb8aa3b, v68
	v_mul_f32_e32 v75, 0xbfb8aa3b, v69
	v_exp_f32_e32 v74, v74
	v_exp_f32_e32 v75, v75
	v_add_f32_e32 v74, 1.0, v74
	v_add_f32_e32 v75, 1.0, v75
	v_rcp_f32_e32 v74, v74
	v_rcp_f32_e32 v75, v75
	s_nop 0
	v_pk_mul_f32 v[68:69], v[68:69], v[74:75]
	s_nop 0
	v_pk_mul_f32 v[64:65], v[68:69], v[64:65]
	s_nop 0
	v_cvt_pk_bf16_f32 v74, v64, v65
	v_mul_f32_e32 v64, 0xbfb8aa3b, v70
	v_mul_f32_e32 v65, 0xbfb8aa3b, v71
	v_exp_f32_e32 v64, v64
	v_exp_f32_e32 v65, v65
	v_add_f32_e32 v64, 1.0, v64
	v_add_f32_e32 v65, 1.0, v65
	v_rcp_f32_e32 v64, v64
	v_rcp_f32_e32 v65, v65
	s_nop 0
	v_pk_mul_f32 v[64:65], v[70:71], v[64:65]
	s_nop 0
	v_pk_mul_f32 v[64:65], v[64:65], v[66:67]
	v_mul_f32_e32 v66, 0xbfb8aa3b, v60
	v_mul_f32_e32 v67, 0xbfb8aa3b, v61
	v_exp_f32_e32 v66, v66
	v_exp_f32_e32 v67, v67
	v_cvt_pk_bf16_f32 v75, v64, v65
	v_add_u32_e32 v64, 0x80, v146
	v_add_f32_e32 v66, 1.0, v66
	v_add_f32_e32 v67, 1.0, v67
	v_rcp_f32_e32 v66, v66
	v_rcp_f32_e32 v67, v67
	v_mad_i64_i32 v[64:65], s[2:3], v64, s48, v[138:139]
	v_lshl_add_u64 v[64:65], v[64:65], 0, v[140:141]
	v_pk_mul_f32 v[60:61], v[60:61], v[66:67]
	global_store_dwordx4 v[80:81], v[72:75], off sc1
	v_pk_mul_f32 v[56:57], v[60:61], v[56:57]
	s_nop 0
	v_cvt_pk_bf16_f32 v56, v56, v57
	v_mul_f32_e32 v57, 0xbfb8aa3b, v62
	v_exp_f32_e32 v57, v57
	s_nop 0
	v_add_f32_e32 v57, 1.0, v57
	v_rcp_f32_e32 v60, v57
	v_mul_f32_e32 v57, 0xbfb8aa3b, v63
	v_exp_f32_e32 v57, v57
	s_nop 0
	v_add_f32_e32 v57, 1.0, v57
	v_rcp_f32_e32 v61, v57
	s_nop 0
	v_pk_mul_f32 v[60:61], v[62:63], v[60:61]
	s_nop 0
	v_pk_mul_f32 v[58:59], v[60:61], v[58:59]
	s_nop 0
	v_cvt_pk_bf16_f32 v57, v58, v59
	v_mul_f32_e32 v58, 0xbfb8aa3b, v52
	v_mul_f32_e32 v59, 0xbfb8aa3b, v53
	v_exp_f32_e32 v58, v58
	v_exp_f32_e32 v59, v59
	v_add_f32_e32 v58, 1.0, v58
	v_add_f32_e32 v59, 1.0, v59
	v_rcp_f32_e32 v58, v58
	v_rcp_f32_e32 v59, v59
	s_nop 0
	v_pk_mul_f32 v[52:53], v[52:53], v[58:59]
	s_nop 0
	v_pk_mul_f32 v[48:49], v[52:53], v[48:49]
	s_nop 0
	v_cvt_pk_bf16_f32 v58, v48, v49
	v_mul_f32_e32 v48, 0xbfb8aa3b, v54
	v_mul_f32_e32 v49, 0xbfb8aa3b, v55
	v_exp_f32_e32 v48, v48
	v_exp_f32_e32 v49, v49
	v_add_f32_e32 v48, 1.0, v48
	v_add_f32_e32 v49, 1.0, v49
	v_rcp_f32_e32 v48, v48
	v_rcp_f32_e32 v49, v49
	s_nop 0
	v_pk_mul_f32 v[48:49], v[54:55], v[48:49]
	s_nop 0
	v_pk_mul_f32 v[48:49], v[48:49], v[50:51]
	v_mul_f32_e32 v50, 0xbfb8aa3b, v44
	v_mul_f32_e32 v51, 0xbfb8aa3b, v45
	v_exp_f32_e32 v50, v50
	v_exp_f32_e32 v51, v51
	v_cvt_pk_bf16_f32 v59, v48, v49
	v_add_u32_e32 v48, 0x90, v146
	v_add_f32_e32 v50, 1.0, v50
	v_add_f32_e32 v51, 1.0, v51
	v_rcp_f32_e32 v50, v50
	v_rcp_f32_e32 v51, v51
	v_mad_i64_i32 v[48:49], s[2:3], v48, s48, v[138:139]
	v_lshl_add_u64 v[48:49], v[48:49], 0, v[140:141]
	v_pk_mul_f32 v[44:45], v[44:45], v[50:51]
	global_store_dwordx4 v[64:65], v[56:59], off sc1
	v_pk_mul_f32 v[40:41], v[44:45], v[40:41]
	s_nop 0
	v_cvt_pk_bf16_f32 v40, v40, v41
	v_mul_f32_e32 v41, 0xbfb8aa3b, v46
	v_exp_f32_e32 v41, v41
	s_nop 0
	v_add_f32_e32 v41, 1.0, v41
	v_rcp_f32_e32 v44, v41
	v_mul_f32_e32 v41, 0xbfb8aa3b, v47
	v_exp_f32_e32 v41, v41
	s_nop 0
	v_add_f32_e32 v41, 1.0, v41
	v_rcp_f32_e32 v45, v41
	s_nop 0
	v_pk_mul_f32 v[44:45], v[46:47], v[44:45]
	s_nop 0
	v_pk_mul_f32 v[42:43], v[44:45], v[42:43]
	s_nop 0
	v_cvt_pk_bf16_f32 v41, v42, v43
	v_mul_f32_e32 v42, 0xbfb8aa3b, v36
	v_mul_f32_e32 v43, 0xbfb8aa3b, v37
	v_exp_f32_e32 v42, v42
; __device__ __forceinline__ unsigned cvt_pk_bf16(float lo, float hi) { const cvt_f32x2 v = {lo, hi}; return __builtin_bit_cast(unsigned, __builtin_convertvector(v, cvt_bf16x2)); }
; __device__ __forceinline__ float silu_mul(float a, float b) { return a * __builtin_amdgcn_rcpf(1.0f + __builtin_amdgcn_exp2f(-1.4426950408889634f * a)) * b; }
;     __device__ __forceinline__ void operator()(const f32x4 (&acc)[2][2][4][2], const Unit& u, int wr, int wc, int fr, int fq) const {
;     ...
;             for (int m = 0; m < 4; ++m) { bf16_t* rowp = O + (size_t)(row0 + ai * HALF + m * 16) * ldc + col0;
;                 const f32x4 a0 = acc[ai][0][m][0], a1 = acc[ai][0][m][1], b0 = acc[ai][1][m][0], b1 = acc[ai][1][m][1];
;                 u32x4 w; w.x = cvt_pk_bf16(silu_mul(a0[0], b0[0]), silu_mul(a0[1], b0[1])); w.y = cvt_pk_bf16(silu_mul(a0[2], b0[2]), silu_mul(a0[3], b0[3]));
;                 w.z = cvt_pk_bf16(silu_mul(a1[0], b1[0]), silu_mul(a1[1], b1[1])); w.w = cvt_pk_bf16(silu_mul(a1[2], b1[2]), silu_mul(a1[3], b1[3]));
;                 *(u32x4*)rowp = w; }
	v_exp_f32_e32 v43, v43
	v_add_f32_e32 v42, 1.0, v42
	v_add_f32_e32 v43, 1.0, v43
	v_rcp_f32_e32 v42, v42
	v_rcp_f32_e32 v43, v43
	s_nop 0
	v_pk_mul_f32 v[36:37], v[36:37], v[42:43]
	s_nop 0
	v_pk_mul_f32 v[32:33], v[36:37], v[32:33]
	s_nop 0
	v_cvt_pk_bf16_f32 v42, v32, v33
	v_mul_f32_e32 v32, 0xbfb8aa3b, v38
	v_mul_f32_e32 v33, 0xbfb8aa3b, v39
	v_exp_f32_e32 v32, v32
	v_exp_f32_e32 v33, v33
	v_add_f32_e32 v32, 1.0, v32
	v_add_f32_e32 v33, 1.0, v33
	v_rcp_f32_e32 v32, v32
	v_rcp_f32_e32 v33, v33
	s_nop 0
	v_pk_mul_f32 v[32:33], v[38:39], v[32:33]
	s_nop 0
	v_pk_mul_f32 v[32:33], v[32:33], v[34:35]
	v_mul_f32_e32 v34, 0xbfb8aa3b, v28
	v_mul_f32_e32 v35, 0xbfb8aa3b, v29
	v_exp_f32_e32 v34, v34
	v_exp_f32_e32 v35, v35
	v_cvt_pk_bf16_f32 v43, v32, v33
	v_add_u32_e32 v32, 0xa0, v146
	v_add_f32_e32 v34, 1.0, v34
	v_add_f32_e32 v35, 1.0, v35
	v_rcp_f32_e32 v34, v34
	v_rcp_f32_e32 v35, v35
	v_mad_i64_i32 v[32:33], s[2:3], v32, s48, v[138:139]
	v_lshl_add_u64 v[32:33], v[32:33], 0, v[140:141]
	v_pk_mul_f32 v[28:29], v[28:29], v[34:35]
	global_store_dwordx4 v[48:49], v[40:43], off sc1
	v_pk_mul_f32 v[24:25], v[28:29], v[24:25]
	s_nop 0
	v_cvt_pk_bf16_f32 v24, v24, v25
	v_mul_f32_e32 v25, 0xbfb8aa3b, v30
	v_exp_f32_e32 v25, v25
	s_nop 0
	v_add_f32_e32 v25, 1.0, v25
	v_rcp_f32_e32 v28, v25
	v_mul_f32_e32 v25, 0xbfb8aa3b, v31
	v_exp_f32_e32 v25, v25
	s_nop 0
	v_add_f32_e32 v25, 1.0, v25
	v_rcp_f32_e32 v29, v25
	s_nop 0
	v_pk_mul_f32 v[28:29], v[30:31], v[28:29]
	s_nop 0
	v_pk_mul_f32 v[26:27], v[28:29], v[26:27]
	s_nop 0
	v_cvt_pk_bf16_f32 v25, v26, v27
	v_mul_f32_e32 v26, 0xbfb8aa3b, v20
	v_mul_f32_e32 v27, 0xbfb8aa3b, v21
	v_exp_f32_e32 v26, v26
	v_exp_f32_e32 v27, v27
	v_add_f32_e32 v26, 1.0, v26
	v_add_f32_e32 v27, 1.0, v27
	v_rcp_f32_e32 v26, v26
	v_rcp_f32_e32 v27, v27
	s_nop 0
	v_pk_mul_f32 v[20:21], v[20:21], v[26:27]
	s_nop 0
	v_pk_mul_f32 v[16:17], v[20:21], v[16:17]
	s_nop 0
	v_cvt_pk_bf16_f32 v26, v16, v17
	v_mul_f32_e32 v16, 0xbfb8aa3b, v22
	v_mul_f32_e32 v17, 0xbfb8aa3b, v23
	v_exp_f32_e32 v16, v16
	v_exp_f32_e32 v17, v17
	v_add_f32_e32 v16, 1.0, v16
	v_add_f32_e32 v17, 1.0, v17
	v_rcp_f32_e32 v16, v16
	v_rcp_f32_e32 v17, v17
	s_nop 0
	v_pk_mul_f32 v[16:17], v[22:23], v[16:17]
	s_nop 0
	v_pk_mul_f32 v[16:17], v[16:17], v[18:19]
	v_mul_f32_e32 v18, 0xbfb8aa3b, v12
	v_mul_f32_e32 v19, 0xbfb8aa3b, v13
	v_exp_f32_e32 v18, v18
	v_exp_f32_e32 v19, v19
	v_cvt_pk_bf16_f32 v27, v16, v17
	v_add_u32_e32 v16, 0xb0, v146
	v_add_f32_e32 v18, 1.0, v18
	v_add_f32_e32 v19, 1.0, v19
	v_rcp_f32_e32 v18, v18
	v_rcp_f32_e32 v19, v19
	v_mad_i64_i32 v[16:17], s[2:3], v16, s48, v[138:139]
	v_lshl_add_u64 v[16:17], v[16:17], 0, v[140:141]
	v_pk_mul_f32 v[12:13], v[12:13], v[18:19]
	global_store_dwordx4 v[32:33], v[24:27], off sc1
	v_pk_mul_f32 v[8:9], v[12:13], v[8:9]
	s_nop 0
	v_cvt_pk_bf16_f32 v8, v8, v9
	v_mul_f32_e32 v9, 0xbfb8aa3b, v14
	v_exp_f32_e32 v9, v9
	s_nop 0
	v_add_f32_e32 v9, 1.0, v9
	v_rcp_f32_e32 v12, v9
	v_mul_f32_e32 v9, 0xbfb8aa3b, v15
	v_exp_f32_e32 v9, v9
	s_nop 0
	v_add_f32_e32 v9, 1.0, v9
	v_rcp_f32_e32 v13, v9
	s_nop 0
	v_pk_mul_f32 v[12:13], v[14:15], v[12:13]
	s_nop 0
	v_pk_mul_f32 v[10:11], v[12:13], v[10:11]
	s_nop 0
	v_cvt_pk_bf16_f32 v9, v10, v11
	v_mul_f32_e32 v10, 0xbfb8aa3b, v4
	v_mul_f32_e32 v11, 0xbfb8aa3b, v5
	v_exp_f32_e32 v10, v10
	v_exp_f32_e32 v11, v11
	v_add_f32_e32 v10, 1.0, v10
	v_add_f32_e32 v11, 1.0, v11
	v_rcp_f32_e32 v10, v10
	v_rcp_f32_e32 v11, v11
	s_nop 0
	v_pk_mul_f32 v[4:5], v[4:5], v[10:11]
	s_nop 0
	v_pk_mul_f32 v[0:1], v[4:5], v[0:1]
	s_nop 0
	v_cvt_pk_bf16_f32 v10, v0, v1
	v_mul_f32_e32 v0, 0xbfb8aa3b, v6
	v_mul_f32_e32 v1, 0xbfb8aa3b, v7
	v_exp_f32_e32 v0, v0
	v_exp_f32_e32 v1, v1
	v_add_f32_e32 v0, 1.0, v0
	v_add_f32_e32 v1, 1.0, v1
	v_rcp_f32_e32 v0, v0
	v_rcp_f32_e32 v1, v1
	s_nop 0
	v_pk_mul_f32 v[0:1], v[6:7], v[0:1]
	s_nop 0
	v_pk_mul_f32 v[0:1], v[0:1], v[2:3]
	s_nop 0
	v_cvt_pk_bf16_f32 v11, v0, v1
	global_store_dwordx4 v[16:17], v[8:11], off sc1
	s_cbranch_vccnz .LBB0_305
	s_andn2_b64 vcc, exec, s[14:15]
	s_cbranch_vccnz .LBB0_304
	s_barrier
	s_branch .LBB0_304
